# static priority mirror: s_setprio 1 once for waves 0-3, all per-cluster flips deleted
# baseline (speedup 1.0000x reference)
_Z6mk_fwd4Args:
	s_load_dwordx8 s[4:11], s[0:1], 0xc0
	s_load_dwordx4 s[76:79], s[0:1], 0xe0
	s_load_dword s3, s[0:1], 0xf8
	v_readfirstlane_b32 s96, v0
	s_nop 3
	s_cmp_ge_u32 s96, 0x100
	s_cbranch_scc1 .Lprio_done
	s_setprio 1
